# v006 + attention B bias table: six relb loads per thread issued together instead of one dependent load per loop trip
# speedup vs baseline: 1.0151x; 1.0035x over previous
.LBB0_380:
	s_and_b32 s30, s28, 7
	s_mul_i32 s4, s30, 0x201
	s_mov_b64 s[12:13], 0
	v_mov_b32_e32 v0, v111
	v_mov_b32_e32 v1, v110
	v_mov_b32_e32 v2, v215
	s_barrier
	v_mul_hi_u32 v3, v215, s21
	v_lshrrev_b32_e32 v3, 9, v3
	v_sub_u32_e32 v4, v110, v3
	v_mad_u32_u24 v4, v3, s22, v4
	v_med3_i32 v4, v4, s23, v114
	v_add_u32_e32 v4, s4, v4
	v_ashrrev_i32_e32 v5, 31, v4
	v_lshl_add_u64 v[4:5], v[4:5], 2, s[66:67]
	global_load_dword v16, v[4:5], off offset:1024
	v_add_u32_e32 v2, 0x200, v215
	v_mul_hi_u32 v3, v2, s21
	v_lshrrev_b32_e32 v3, 9, v3
	v_sub_u32_e32 v6, v110, v3
	v_add_u32_e32 v6, 0xfffffe00, v6
	v_mad_u32_u24 v6, v3, s22, v6
	v_med3_i32 v6, v6, s23, v114
	v_add_u32_e32 v6, s4, v6
	v_ashrrev_i32_e32 v7, 31, v6
	v_lshl_add_u64 v[6:7], v[6:7], 2, s[66:67]
	global_load_dword v17, v[6:7], off offset:1024
	v_add_u32_e32 v2, 0x400, v215
	v_mul_hi_u32 v3, v2, s21
	v_lshrrev_b32_e32 v3, 9, v3
	v_sub_u32_e32 v8, v110, v3
	v_add_u32_e32 v8, 0xfffffc00, v8
	v_mad_u32_u24 v8, v3, s22, v8
	v_med3_i32 v8, v8, s23, v114
	v_add_u32_e32 v8, s4, v8
	v_ashrrev_i32_e32 v9, 31, v8
	v_lshl_add_u64 v[8:9], v[8:9], 2, s[66:67]
	global_load_dword v18, v[8:9], off offset:1024
	v_add_u32_e32 v2, 0x600, v215
	v_mul_hi_u32 v3, v2, s21
	v_lshrrev_b32_e32 v3, 9, v3
	v_sub_u32_e32 v10, v110, v3
	v_add_u32_e32 v10, 0xfffffa00, v10
	v_mad_u32_u24 v10, v3, s22, v10
	v_med3_i32 v10, v10, s23, v114
	v_add_u32_e32 v10, s4, v10
	v_ashrrev_i32_e32 v11, 31, v10
	v_lshl_add_u64 v[10:11], v[10:11], 2, s[66:67]
	global_load_dword v19, v[10:11], off offset:1024
	v_add_u32_e32 v2, 0x800, v215
	v_mul_hi_u32 v3, v2, s21
	v_lshrrev_b32_e32 v3, 9, v3
	v_sub_u32_e32 v12, v110, v3
	v_add_u32_e32 v12, 0xfffff800, v12
	v_mad_u32_u24 v12, v3, s22, v12
	v_med3_i32 v12, v12, s23, v114
	v_add_u32_e32 v12, s4, v12
	v_ashrrev_i32_e32 v13, 31, v12
	v_lshl_add_u64 v[12:13], v[12:13], 2, s[66:67]
	global_load_dword v20, v[12:13], off offset:1024
	v_cmp_gt_u32_e32 vcc, 16, v215
	s_and_saveexec_b64 s[12:13], vcc
	v_add_u32_e32 v2, 0xa00, v215
	v_mul_hi_u32 v3, v2, s21
	v_lshrrev_b32_e32 v3, 9, v3
	v_sub_u32_e32 v14, v110, v3
	v_add_u32_e32 v14, 0xfffff600, v14
	v_mad_u32_u24 v14, v3, s22, v14
	v_med3_i32 v14, v14, s23, v114
	v_add_u32_e32 v14, s4, v14
	v_ashrrev_i32_e32 v15, 31, v14
	v_lshl_add_u64 v[14:15], v[14:15], 2, s[66:67]
	global_load_dword v21, v[14:15], off offset:1024
	s_or_b64 exec, exec, s[12:13]
	s_waitcnt vmcnt(0)
	v_mul_f32_e32 v16, 0x3fb8aa3b, v16
	ds_write_b32 v111, v16
	v_mul_f32_e32 v17, 0x3fb8aa3b, v17
	ds_write_b32 v111, v17 offset:2048
	v_mul_f32_e32 v18, 0x3fb8aa3b, v18
	ds_write_b32 v111, v18 offset:4096
	v_mul_f32_e32 v19, 0x3fb8aa3b, v19
	ds_write_b32 v111, v19 offset:6144
	v_mul_f32_e32 v20, 0x3fb8aa3b, v20
	ds_write_b32 v111, v20 offset:8192
	v_cmp_gt_u32_e32 vcc, 16, v215
	s_and_saveexec_b64 s[12:13], vcc
	v_mul_f32_e32 v21, 0x3fb8aa3b, v21
	ds_write_b32 v111, v21 offset:10240
	s_or_b64 exec, exec, s[12:13]
	s_ashr_i32 s13, s28, 7
	s_lshl_b32 s37, s13, 8
	s_lshl_b32 s4, s28, 8
	s_add_i32 s37, s37, s40
	s_lshl_b32 s12, s13, 2
	s_and_b32 s31, s4, 0x7800
	s_ashr_i32 s29, s37, 31
	s_add_u32 s4, s37, s31
	s_addc_u32 s29, s29, 0
	s_mul_i32 s34, s29, 0x1800
	s_mul_hi_u32 s35, s4, 0x1800
	s_add_i32 s35, s35, s34
	s_mul_i32 s34, s4, 0x1800
	s_add_u32 s34, s10, s34
	s_addc_u32 s35, s11, s35
	s_lshl_b32 s36, s30, 7
	s_add_u32 s34, s34, s36
	s_addc_u32 s35, s35, 0
	v_lshl_add_u64 v[0:1], s[34:35], 0, v[132:133]
	v_lshl_add_u64 v[0:1], v[0:1], 0, v[134:135]
	global_load_dwordx4 v[64:67], v[0:1], off offset:3072
	global_load_dwordx4 v[68:71], v[0:1], off offset:3104
	global_load_dwordx4 v[72:75], v[0:1], off offset:3136
	global_load_dwordx4 v[76:79], v[0:1], off offset:3168
	s_mulk_i32 s31, 0x1800
	s_add_u32 s31, s10, s31
	s_addc_u32 s35, s11, 0
	s_add_u32 s31, s31, s36
	s_addc_u32 s35, s35, 0
	s_add_u32 s43, s31, 0x1000
	s_addc_u32 s44, s35, 0
	v_readfirstlane_b32 s34, v215
	s_add_u32 s36, s31, 0x1400
	s_addc_u32 s38, s35, 0
	s_max_i32 s42, s12, 8
	s_lshr_b32 s39, s34, 6
	s_add_i32 s35, s42, -8
	v_lshl_or_b32 v0, s39, 3, v172
	s_add_i32 s31, s12, 4
	v_lshrrev_b32_e32 v2, 1, v0
	s_mul_i32 s54, s35, 0x60000
	s_mul_hi_u32 s45, s35, 0x60000
	v_xor_b32_e32 v2, v2, v215
	s_add_u32 s52, s43, s54
	v_lshlrev_b32_e32 v2, 3, v2
	s_addc_u32 s53, s44, s45
	s_lshl_b32 s34, s39, 10
	v_mul_lo_u32 v3, v0, s18
	v_and_b32_e32 v32, 56, v2
	s_add_i32 s34, s34, 0
	v_or_b32_e32 v98, v32, v3
	s_add_u32 s54, s36, s54
	v_mov_b32_e32 v1, v99
	s_waitcnt vmcnt(0)
	v_or_b32_e32 v0, v115, v3
	v_lshl_add_u64 v[2:3], v[98:99], 1, s[52:53]
	s_addc_u32 s55, s38, s45
	s_mov_b32 m0, s34
	v_lshl_add_u64 v[4:5], v[0:1], 1, s[54:55]
	s_add_i32 s45, s42, -7
	s_waitcnt vmcnt(3)
	s_waitcnt vmcnt(2)
	s_waitcnt vmcnt(1)
	s_waitcnt vmcnt(0)
	s_barrier
	global_load_lds_dwordx4 v[2:3], off
	s_add_i32 m0, s34, 0x2000
	s_cmp_ge_i32 s45, s31
	global_load_lds_dwordx4 v[4:5], off
	s_cbranch_scc1 .LBB0_384
	s_mul_hi_u32 s54, s45, 0x60000
	s_mul_i32 s45, s45, 0x60000
	s_add_u32 s52, s43, s45
	s_addc_u32 s53, s44, s54
	s_add_i32 m0, s34, 0x4000
	v_lshl_add_u64 v[2:3], v[98:99], 1, s[52:53]
	s_add_u32 s52, s36, s45
	s_addc_u32 s53, s38, s54
	global_load_lds_dwordx4 v[2:3], off
	v_lshl_add_u64 v[2:3], v[0:1], 1, s[52:53]
	s_add_i32 m0, s34, 0x6000
	s_nop 0
	global_load_lds_dwordx4 v[2:3], off
